# fused layer-1 epilogue: gates and first residual groups fetched before the row-sum exchange instead of after
# speedup vs baseline: 1.0108x; 1.0024x over previous
.Lgo_fz_epi:
	s_nop 7
	s_nop 7
	s_load_dwordx2 s[94:95], s[88:89], 0x168
	s_load_dwordx2 s[98:99], s[88:89], 0x170
	s_load_dwordx2 s[2:3], s[88:89], 0xc0
	v_and_b32_e32 v160, 15, v167
	v_bfe_u32 v161, v167, 4, 2
	v_bfe_u32 v162, v167, 6, 2
	v_lshrrev_b32_e32 v163, 8, v167
	v_lshlrev_b32_e32 v163, 6, v163
	v_lshl_add_u32 v163, v161, 2, v163
	v_lshl_add_u32 v164, v162, 5, v160
	s_lshr_b32 s45, s36, 8
	s_lshr_b32 s48, s34, 8
	s_lshr_b32 s57, s36, 12
	s_add_u32 s57, s57, 5
	s_mul_i32 s57, s57, 0x6000
	s_add_u32 s57, s57, 0x4000
	v_lshlrev_b32_e32 v237, 2, v164
	s_lshl_b32 s0, s34, 2
	v_add_u32_e32 v237, s0, v237
	v_add_u32_e32 v168, s36, v163
	v_lshlrev_b32_e32 v168, 13, v168
	v_add_u32_e32 v168, v168, v237
	v_add_u32_e32 v169, 0x2000, v168
	v_add_u32_e32 v170, 0x4000, v168
	v_add_u32_e32 v171, 0x6000, v168
	s_load_dwordx2 s[36:37], s[88:89], 0xc8
	s_load_dwordx2 s[34:35], s[88:89], 0xf0
	v_mul_f32_e32 v194, v124, v124
	v_fmac_f32_e32 v194, v120, v120
	v_fmac_f32_e32 v194, v100, v100
	v_fmac_f32_e32 v194, v96, v96
	v_mul_f32_e32 v195, v125, v125
	v_fmac_f32_e32 v195, v121, v121
	v_fmac_f32_e32 v195, v101, v101
	v_fmac_f32_e32 v195, v97, v97
	v_mul_f32_e32 v196, v126, v126
	v_fmac_f32_e32 v196, v122, v122
	v_fmac_f32_e32 v196, v102, v102
	v_fmac_f32_e32 v196, v98, v98
	v_mul_f32_e32 v197, v127, v127
	v_fmac_f32_e32 v197, v123, v123
	v_fmac_f32_e32 v197, v103, v103
	v_fmac_f32_e32 v197, v99, v99
	v_mul_f32_e32 v198, v116, v116
	v_fmac_f32_e32 v198, v112, v112
	v_fmac_f32_e32 v198, v92, v92
	v_fmac_f32_e32 v198, v88, v88
	v_mul_f32_e32 v199, v117, v117
	v_fmac_f32_e32 v199, v113, v113
	v_fmac_f32_e32 v199, v93, v93
	v_fmac_f32_e32 v199, v89, v89
	v_mul_f32_e32 v200, v118, v118
	v_fmac_f32_e32 v200, v114, v114
	v_fmac_f32_e32 v200, v94, v94
	v_fmac_f32_e32 v200, v90, v90
	v_mul_f32_e32 v201, v119, v119
	v_fmac_f32_e32 v201, v115, v115
	v_fmac_f32_e32 v201, v95, v95
	v_fmac_f32_e32 v201, v91, v91
	v_mul_f32_e32 v202, v108, v108
	v_fmac_f32_e32 v202, v104, v104
	v_fmac_f32_e32 v202, v80, v80
	v_fmac_f32_e32 v202, v72, v72
	v_mul_f32_e32 v203, v109, v109
	v_fmac_f32_e32 v203, v105, v105
	v_fmac_f32_e32 v203, v81, v81
	v_fmac_f32_e32 v203, v73, v73
	v_mul_f32_e32 v204, v110, v110
	v_fmac_f32_e32 v204, v106, v106
	v_fmac_f32_e32 v204, v82, v82
	v_fmac_f32_e32 v204, v74, v74
	v_mul_f32_e32 v205, v111, v111
	v_fmac_f32_e32 v205, v107, v107
	v_fmac_f32_e32 v205, v83, v83
	v_fmac_f32_e32 v205, v75, v75
	v_mul_f32_e32 v206, v84, v84
	v_fmac_f32_e32 v206, v76, v76
	v_fmac_f32_e32 v206, v68, v68
	v_fmac_f32_e32 v206, v64, v64
	v_mul_f32_e32 v207, v85, v85
	v_fmac_f32_e32 v207, v77, v77
	v_fmac_f32_e32 v207, v69, v69
	v_fmac_f32_e32 v207, v65, v65
	v_mul_f32_e32 v208, v86, v86
	v_fmac_f32_e32 v208, v78, v78
	v_fmac_f32_e32 v208, v70, v70
	v_fmac_f32_e32 v208, v66, v66
	v_mul_f32_e32 v209, v87, v87
	v_fmac_f32_e32 v209, v79, v79
	v_fmac_f32_e32 v209, v71, v71
	v_fmac_f32_e32 v209, v67, v67
	v_mul_f32_e32 v210, v60, v60
	v_fmac_f32_e32 v210, v56, v56
	v_fmac_f32_e32 v210, v32, v32
	v_fmac_f32_e32 v210, v24, v24
	v_mul_f32_e32 v211, v61, v61
	v_fmac_f32_e32 v211, v57, v57
	v_fmac_f32_e32 v211, v33, v33
	v_fmac_f32_e32 v211, v25, v25
	v_mul_f32_e32 v212, v62, v62
	v_fmac_f32_e32 v212, v58, v58
	v_fmac_f32_e32 v212, v34, v34
	v_fmac_f32_e32 v212, v26, v26
	v_mul_f32_e32 v213, v63, v63
	v_fmac_f32_e32 v213, v59, v59
	v_fmac_f32_e32 v213, v35, v35
	v_fmac_f32_e32 v213, v27, v27
	v_mul_f32_e32 v214, v52, v52
	v_fmac_f32_e32 v214, v48, v48
	v_fmac_f32_e32 v214, v20, v20
	v_fmac_f32_e32 v214, v16, v16
	v_mul_f32_e32 v215, v53, v53
	v_fmac_f32_e32 v215, v49, v49
	v_fmac_f32_e32 v215, v21, v21
	v_fmac_f32_e32 v215, v17, v17
	v_mul_f32_e32 v216, v54, v54
	v_fmac_f32_e32 v216, v50, v50
	v_fmac_f32_e32 v216, v22, v22
	v_fmac_f32_e32 v216, v18, v18
	v_mul_f32_e32 v217, v55, v55
	v_fmac_f32_e32 v217, v51, v51
	v_fmac_f32_e32 v217, v23, v23
	v_fmac_f32_e32 v217, v19, v19
	v_mul_f32_e32 v218, v44, v44
	v_fmac_f32_e32 v218, v40, v40
	v_fmac_f32_e32 v218, v12, v12
	v_fmac_f32_e32 v218, v8, v8
	v_mul_f32_e32 v219, v45, v45
	v_fmac_f32_e32 v219, v41, v41
	v_fmac_f32_e32 v219, v13, v13
	v_fmac_f32_e32 v219, v9, v9
	v_mul_f32_e32 v220, v46, v46
	v_fmac_f32_e32 v220, v42, v42
	v_fmac_f32_e32 v220, v14, v14
	v_fmac_f32_e32 v220, v10, v10
	v_mul_f32_e32 v221, v47, v47
	v_fmac_f32_e32 v221, v43, v43
	v_fmac_f32_e32 v221, v15, v15
	v_fmac_f32_e32 v221, v11, v11
	v_mul_f32_e32 v222, v36, v36
	v_fmac_f32_e32 v222, v28, v28
	v_fmac_f32_e32 v222, v4, v4
	v_fmac_f32_e32 v222, v0, v0
	v_mul_f32_e32 v223, v37, v37
	v_fmac_f32_e32 v223, v29, v29
	v_fmac_f32_e32 v223, v5, v5
	v_fmac_f32_e32 v223, v1, v1
	v_mul_f32_e32 v224, v38, v38
	v_fmac_f32_e32 v224, v30, v30
	v_fmac_f32_e32 v224, v6, v6
	v_fmac_f32_e32 v224, v2, v2
	v_mul_f32_e32 v225, v39, v39
	v_fmac_f32_e32 v225, v31, v31
	v_fmac_f32_e32 v225, v7, v7
	v_fmac_f32_e32 v225, v3, v3
	s_nop 1
	v_add_f32_dpp v194, v194, v194 row_ror:8 row_mask:0xf bank_mask:0xf
	v_add_f32_dpp v195, v195, v195 row_ror:8 row_mask:0xf bank_mask:0xf
	v_add_f32_dpp v196, v196, v196 row_ror:8 row_mask:0xf bank_mask:0xf
	v_add_f32_dpp v197, v197, v197 row_ror:8 row_mask:0xf bank_mask:0xf
	v_add_f32_dpp v198, v198, v198 row_ror:8 row_mask:0xf bank_mask:0xf
	v_add_f32_dpp v199, v199, v199 row_ror:8 row_mask:0xf bank_mask:0xf
	v_add_f32_dpp v200, v200, v200 row_ror:8 row_mask:0xf bank_mask:0xf
	v_add_f32_dpp v201, v201, v201 row_ror:8 row_mask:0xf bank_mask:0xf
	v_add_f32_dpp v202, v202, v202 row_ror:8 row_mask:0xf bank_mask:0xf
	v_add_f32_dpp v203, v203, v203 row_ror:8 row_mask:0xf bank_mask:0xf
	v_add_f32_dpp v204, v204, v204 row_ror:8 row_mask:0xf bank_mask:0xf
	v_add_f32_dpp v205, v205, v205 row_ror:8 row_mask:0xf bank_mask:0xf
	v_add_f32_dpp v206, v206, v206 row_ror:8 row_mask:0xf bank_mask:0xf
	v_add_f32_dpp v207, v207, v207 row_ror:8 row_mask:0xf bank_mask:0xf
	v_add_f32_dpp v208, v208, v208 row_ror:8 row_mask:0xf bank_mask:0xf
	v_add_f32_dpp v209, v209, v209 row_ror:8 row_mask:0xf bank_mask:0xf
	v_add_f32_dpp v210, v210, v210 row_ror:8 row_mask:0xf bank_mask:0xf
	v_add_f32_dpp v211, v211, v211 row_ror:8 row_mask:0xf bank_mask:0xf
	v_add_f32_dpp v212, v212, v212 row_ror:8 row_mask:0xf bank_mask:0xf
	v_add_f32_dpp v213, v213, v213 row_ror:8 row_mask:0xf bank_mask:0xf
	v_add_f32_dpp v214, v214, v214 row_ror:8 row_mask:0xf bank_mask:0xf
	v_add_f32_dpp v215, v215, v215 row_ror:8 row_mask:0xf bank_mask:0xf
	v_add_f32_dpp v216, v216, v216 row_ror:8 row_mask:0xf bank_mask:0xf
	v_add_f32_dpp v217, v217, v217 row_ror:8 row_mask:0xf bank_mask:0xf
	v_add_f32_dpp v218, v218, v218 row_ror:8 row_mask:0xf bank_mask:0xf
	v_add_f32_dpp v219, v219, v219 row_ror:8 row_mask:0xf bank_mask:0xf
	v_add_f32_dpp v220, v220, v220 row_ror:8 row_mask:0xf bank_mask:0xf
	v_add_f32_dpp v221, v221, v221 row_ror:8 row_mask:0xf bank_mask:0xf
	v_add_f32_dpp v222, v222, v222 row_ror:8 row_mask:0xf bank_mask:0xf
	v_add_f32_dpp v223, v223, v223 row_ror:8 row_mask:0xf bank_mask:0xf
	v_add_f32_dpp v224, v224, v224 row_ror:8 row_mask:0xf bank_mask:0xf
	v_add_f32_dpp v225, v225, v225 row_ror:8 row_mask:0xf bank_mask:0xf
	s_nop 1
	v_add_f32_dpp v194, v194, v194 row_ror:4 row_mask:0xf bank_mask:0xf
	v_add_f32_dpp v195, v195, v195 row_ror:4 row_mask:0xf bank_mask:0xf
	v_add_f32_dpp v196, v196, v196 row_ror:4 row_mask:0xf bank_mask:0xf
	v_add_f32_dpp v197, v197, v197 row_ror:4 row_mask:0xf bank_mask:0xf
	v_add_f32_dpp v198, v198, v198 row_ror:4 row_mask:0xf bank_mask:0xf
	v_add_f32_dpp v199, v199, v199 row_ror:4 row_mask:0xf bank_mask:0xf
	v_add_f32_dpp v200, v200, v200 row_ror:4 row_mask:0xf bank_mask:0xf
	v_add_f32_dpp v201, v201, v201 row_ror:4 row_mask:0xf bank_mask:0xf
	v_add_f32_dpp v202, v202, v202 row_ror:4 row_mask:0xf bank_mask:0xf
	v_add_f32_dpp v203, v203, v203 row_ror:4 row_mask:0xf bank_mask:0xf
	v_add_f32_dpp v204, v204, v204 row_ror:4 row_mask:0xf bank_mask:0xf
	v_add_f32_dpp v205, v205, v205 row_ror:4 row_mask:0xf bank_mask:0xf
	v_add_f32_dpp v206, v206, v206 row_ror:4 row_mask:0xf bank_mask:0xf
	v_add_f32_dpp v207, v207, v207 row_ror:4 row_mask:0xf bank_mask:0xf
	v_add_f32_dpp v208, v208, v208 row_ror:4 row_mask:0xf bank_mask:0xf
	v_add_f32_dpp v209, v209, v209 row_ror:4 row_mask:0xf bank_mask:0xf
	v_add_f32_dpp v210, v210, v210 row_ror:4 row_mask:0xf bank_mask:0xf
	v_add_f32_dpp v211, v211, v211 row_ror:4 row_mask:0xf bank_mask:0xf
	v_add_f32_dpp v212, v212, v212 row_ror:4 row_mask:0xf bank_mask:0xf
	v_add_f32_dpp v213, v213, v213 row_ror:4 row_mask:0xf bank_mask:0xf
	v_add_f32_dpp v214, v214, v214 row_ror:4 row_mask:0xf bank_mask:0xf
	v_add_f32_dpp v215, v215, v215 row_ror:4 row_mask:0xf bank_mask:0xf
	v_add_f32_dpp v216, v216, v216 row_ror:4 row_mask:0xf bank_mask:0xf
	v_add_f32_dpp v217, v217, v217 row_ror:4 row_mask:0xf bank_mask:0xf
	v_add_f32_dpp v218, v218, v218 row_ror:4 row_mask:0xf bank_mask:0xf
	v_add_f32_dpp v219, v219, v219 row_ror:4 row_mask:0xf bank_mask:0xf
	v_add_f32_dpp v220, v220, v220 row_ror:4 row_mask:0xf bank_mask:0xf
	v_add_f32_dpp v221, v221, v221 row_ror:4 row_mask:0xf bank_mask:0xf
	v_add_f32_dpp v222, v222, v222 row_ror:4 row_mask:0xf bank_mask:0xf
	v_add_f32_dpp v223, v223, v223 row_ror:4 row_mask:0xf bank_mask:0xf
	v_add_f32_dpp v224, v224, v224 row_ror:4 row_mask:0xf bank_mask:0xf
	v_add_f32_dpp v225, v225, v225 row_ror:4 row_mask:0xf bank_mask:0xf
	s_nop 1
	v_add_f32_dpp v194, v194, v194 row_ror:2 row_mask:0xf bank_mask:0xf
	v_add_f32_dpp v195, v195, v195 row_ror:2 row_mask:0xf bank_mask:0xf
	v_add_f32_dpp v196, v196, v196 row_ror:2 row_mask:0xf bank_mask:0xf
	v_add_f32_dpp v197, v197, v197 row_ror:2 row_mask:0xf bank_mask:0xf
	v_add_f32_dpp v198, v198, v198 row_ror:2 row_mask:0xf bank_mask:0xf
	v_add_f32_dpp v199, v199, v199 row_ror:2 row_mask:0xf bank_mask:0xf
	v_add_f32_dpp v200, v200, v200 row_ror:2 row_mask:0xf bank_mask:0xf
	v_add_f32_dpp v201, v201, v201 row_ror:2 row_mask:0xf bank_mask:0xf
	v_add_f32_dpp v202, v202, v202 row_ror:2 row_mask:0xf bank_mask:0xf
	v_add_f32_dpp v203, v203, v203 row_ror:2 row_mask:0xf bank_mask:0xf
	v_add_f32_dpp v204, v204, v204 row_ror:2 row_mask:0xf bank_mask:0xf
	v_add_f32_dpp v205, v205, v205 row_ror:2 row_mask:0xf bank_mask:0xf
	v_add_f32_dpp v206, v206, v206 row_ror:2 row_mask:0xf bank_mask:0xf
	v_add_f32_dpp v207, v207, v207 row_ror:2 row_mask:0xf bank_mask:0xf
	v_add_f32_dpp v208, v208, v208 row_ror:2 row_mask:0xf bank_mask:0xf
	v_add_f32_dpp v209, v209, v209 row_ror:2 row_mask:0xf bank_mask:0xf
	v_add_f32_dpp v210, v210, v210 row_ror:2 row_mask:0xf bank_mask:0xf
	v_add_f32_dpp v211, v211, v211 row_ror:2 row_mask:0xf bank_mask:0xf
	v_add_f32_dpp v212, v212, v212 row_ror:2 row_mask:0xf bank_mask:0xf
	v_add_f32_dpp v213, v213, v213 row_ror:2 row_mask:0xf bank_mask:0xf
	v_add_f32_dpp v214, v214, v214 row_ror:2 row_mask:0xf bank_mask:0xf
	v_add_f32_dpp v215, v215, v215 row_ror:2 row_mask:0xf bank_mask:0xf
	v_add_f32_dpp v216, v216, v216 row_ror:2 row_mask:0xf bank_mask:0xf
	v_add_f32_dpp v217, v217, v217 row_ror:2 row_mask:0xf bank_mask:0xf
	v_add_f32_dpp v218, v218, v218 row_ror:2 row_mask:0xf bank_mask:0xf
	v_add_f32_dpp v219, v219, v219 row_ror:2 row_mask:0xf bank_mask:0xf
	v_add_f32_dpp v220, v220, v220 row_ror:2 row_mask:0xf bank_mask:0xf
	v_add_f32_dpp v221, v221, v221 row_ror:2 row_mask:0xf bank_mask:0xf
	v_add_f32_dpp v222, v222, v222 row_ror:2 row_mask:0xf bank_mask:0xf
	v_add_f32_dpp v223, v223, v223 row_ror:2 row_mask:0xf bank_mask:0xf
	v_add_f32_dpp v224, v224, v224 row_ror:2 row_mask:0xf bank_mask:0xf
	v_add_f32_dpp v225, v225, v225 row_ror:2 row_mask:0xf bank_mask:0xf
	s_nop 1
	v_add_f32_dpp v194, v194, v194 row_ror:1 row_mask:0xf bank_mask:0xf
	v_add_f32_dpp v195, v195, v195 row_ror:1 row_mask:0xf bank_mask:0xf
	v_add_f32_dpp v196, v196, v196 row_ror:1 row_mask:0xf bank_mask:0xf
	v_add_f32_dpp v197, v197, v197 row_ror:1 row_mask:0xf bank_mask:0xf
	v_add_f32_dpp v198, v198, v198 row_ror:1 row_mask:0xf bank_mask:0xf
	v_add_f32_dpp v199, v199, v199 row_ror:1 row_mask:0xf bank_mask:0xf
	v_add_f32_dpp v200, v200, v200 row_ror:1 row_mask:0xf bank_mask:0xf
	v_add_f32_dpp v201, v201, v201 row_ror:1 row_mask:0xf bank_mask:0xf
	v_add_f32_dpp v202, v202, v202 row_ror:1 row_mask:0xf bank_mask:0xf
	v_add_f32_dpp v203, v203, v203 row_ror:1 row_mask:0xf bank_mask:0xf
	v_add_f32_dpp v204, v204, v204 row_ror:1 row_mask:0xf bank_mask:0xf
	v_add_f32_dpp v205, v205, v205 row_ror:1 row_mask:0xf bank_mask:0xf
	v_add_f32_dpp v206, v206, v206 row_ror:1 row_mask:0xf bank_mask:0xf
	v_add_f32_dpp v207, v207, v207 row_ror:1 row_mask:0xf bank_mask:0xf
	v_add_f32_dpp v208, v208, v208 row_ror:1 row_mask:0xf bank_mask:0xf
	v_add_f32_dpp v209, v209, v209 row_ror:1 row_mask:0xf bank_mask:0xf
	v_add_f32_dpp v210, v210, v210 row_ror:1 row_mask:0xf bank_mask:0xf
	v_add_f32_dpp v211, v211, v211 row_ror:1 row_mask:0xf bank_mask:0xf
	v_add_f32_dpp v212, v212, v212 row_ror:1 row_mask:0xf bank_mask:0xf
	v_add_f32_dpp v213, v213, v213 row_ror:1 row_mask:0xf bank_mask:0xf
	v_add_f32_dpp v214, v214, v214 row_ror:1 row_mask:0xf bank_mask:0xf
	v_add_f32_dpp v215, v215, v215 row_ror:1 row_mask:0xf bank_mask:0xf
	v_add_f32_dpp v216, v216, v216 row_ror:1 row_mask:0xf bank_mask:0xf
	v_add_f32_dpp v217, v217, v217 row_ror:1 row_mask:0xf bank_mask:0xf
	v_add_f32_dpp v218, v218, v218 row_ror:1 row_mask:0xf bank_mask:0xf
	v_add_f32_dpp v219, v219, v219 row_ror:1 row_mask:0xf bank_mask:0xf
	v_add_f32_dpp v220, v220, v220 row_ror:1 row_mask:0xf bank_mask:0xf
	v_add_f32_dpp v221, v221, v221 row_ror:1 row_mask:0xf bank_mask:0xf
	v_add_f32_dpp v222, v222, v222 row_ror:1 row_mask:0xf bank_mask:0xf
	v_add_f32_dpp v223, v223, v223 row_ror:1 row_mask:0xf bank_mask:0xf
	v_add_f32_dpp v224, v224, v224 row_ror:1 row_mask:0xf bank_mask:0xf
	v_add_f32_dpp v225, v225, v225 row_ror:1 row_mask:0xf bank_mask:0xf
	v_lshlrev_b32_e32 v236, 10, v162
	v_lshl_add_u32 v236, v163, 2, v236
	v_add_u32_e32 v236, 0x20000, v236
	v_cmp_eq_u32_e32 vcc, 0, v160
	s_and_saveexec_b64 s[0:1], vcc
	ds_write_b128 v236, v[194:197]
	ds_write_b128 v236, v[198:201] offset:64
	ds_write_b128 v236, v[202:205] offset:128
	ds_write_b128 v236, v[206:209] offset:192
	ds_write_b128 v236, v[210:213] offset:512
	ds_write_b128 v236, v[214:217] offset:576
	ds_write_b128 v236, v[218:221] offset:640
	ds_write_b128 v236, v[222:225] offset:704
	s_or_b64 exec, exec, s[0:1]
	v_readfirstlane_b32 s32, v167
	s_waitcnt lgkmcnt(0)
	s_add_u32 s34, s34, s57
	s_addc_u32 s35, s35, 0
	s_add_u32 s2, s2, 0x2000
	s_addc_u32 s3, s3, 0
	s_barrier
	s_cmp_lt_u32 s32, 0x100
	s_cbranch_scc0 .Lgo_fz_w1
	v_lshlrev_b32_e32 v238, 2, v167
	v_add_u32_e32 v239, 0x20000, v238
	ds_read_b32 v240, v239
	ds_read_b32 v241, v239 offset:1024
	ds_read_b32 v242, v239 offset:2048
	ds_read_b32 v243, v239 offset:3072
	s_lshl_b32 s1, s45, 3
	s_add_u32 s1, s1, s48
	s_lshl_b32 s1, s1, 10
	v_add_u32_e32 v244, s1, v238
	s_waitcnt lgkmcnt(0)
	v_add_f32_e32 v240, v240, v241
	v_add_f32_e32 v240, v240, v242
	v_add_f32_e32 v240, v240, v243
	global_store_dword v244, v240, s[94:95] sc0 sc1
	s_waitcnt vmcnt(0)
.Lgo_fz_w1:
	s_cmp_lt_u32 s32, 64
	s_cbranch_scc1 .Lgo_fz_nopf
	global_load_dword v226, v237, s[34:35]
	global_load_dword v230, v237, s[2:3]
	global_load_dword v227, v237, s[34:35] offset:64
	global_load_dword v231, v237, s[2:3] offset:64
	global_load_dword v228, v237, s[34:35] offset:512
	global_load_dword v232, v237, s[2:3] offset:512
	global_load_dword v229, v237, s[34:35] offset:576
	global_load_dword v233, v237, s[2:3] offset:576
	v_mov_b32_e32 v172, v168
	v_mov_b32_e32 v173, v169
	v_mov_b32_e32 v174, v170
	v_mov_b32_e32 v175, v171
	global_load_dword v128, v172, s[36:37]
	global_load_dword v129, v173, s[36:37]
	global_load_dword v130, v174, s[36:37]
	global_load_dword v131, v175, s[36:37]
	global_load_dword v132, v172, s[36:37] offset:64
	global_load_dword v133, v173, s[36:37] offset:64
	global_load_dword v134, v174, s[36:37] offset:64
	global_load_dword v135, v175, s[36:37] offset:64
	global_load_dword v136, v172, s[36:37] offset:512
	global_load_dword v137, v173, s[36:37] offset:512
	global_load_dword v138, v174, s[36:37] offset:512
	global_load_dword v139, v175, s[36:37] offset:512
	global_load_dword v140, v172, s[36:37] offset:576
	global_load_dword v141, v173, s[36:37] offset:576
	global_load_dword v142, v174, s[36:37] offset:576
	global_load_dword v143, v175, s[36:37] offset:576
	v_add_u32_e32 v176, 0x20000, v168
	v_add_u32_e32 v177, 0x20000, v169
	v_add_u32_e32 v178, 0x20000, v170
	v_add_u32_e32 v179, 0x20000, v171
	global_load_dword v144, v176, s[36:37]
	global_load_dword v145, v177, s[36:37]
	global_load_dword v146, v178, s[36:37]
	global_load_dword v147, v179, s[36:37]
	global_load_dword v148, v176, s[36:37] offset:64
	global_load_dword v149, v177, s[36:37] offset:64
	global_load_dword v150, v178, s[36:37] offset:64
	global_load_dword v151, v179, s[36:37] offset:64
	global_load_dword v152, v176, s[36:37] offset:512
	global_load_dword v153, v177, s[36:37] offset:512
	global_load_dword v154, v178, s[36:37] offset:512
	global_load_dword v155, v179, s[36:37] offset:512
	global_load_dword v156, v176, s[36:37] offset:576
	global_load_dword v157, v177, s[36:37] offset:576
	global_load_dword v158, v178, s[36:37] offset:576
	global_load_dword v159, v179, s[36:37] offset:576
.Lgo_fz_nopf:
	s_barrier
	s_cmp_lt_u32 s32, 64
	s_cbranch_scc0 .Lgo_fz_w2
	s_lshl_b32 s0, s45, 2
	s_add_u32 s0, s0, 0x204
	v_mov_b32_e32 v245, s0
	v_mov_b32_e32 v246, 1
	s_mov_b64 exec, 1
	global_atomic_add v245, v246, s[98:99]
	s_mov_b32 s57, 0
.Lgo_fz_poll:
	global_load_dword v247, v245, s[98:99] sc1
	s_waitcnt vmcnt(0)
	v_readfirstlane_b32 s1, v247
	s_cmp_ge_u32 s1, 8
	s_cbranch_scc1 .Lgo_fz_got
	s_sleep 1
	s_add_u32 s57, s57, 1
	s_cmp_lt_u32 s57, 0x200000
	s_cbranch_scc1 .Lgo_fz_poll
.Lgo_fz_got:
	s_mov_b64 exec, -1
	buffer_inv sc1
	global_load_dword v226, v237, s[34:35]
	global_load_dword v230, v237, s[2:3]
	global_load_dword v227, v237, s[34:35] offset:64
	global_load_dword v231, v237, s[2:3] offset:64
	global_load_dword v228, v237, s[34:35] offset:512
	global_load_dword v232, v237, s[2:3] offset:512
	global_load_dword v229, v237, s[34:35] offset:576
	global_load_dword v233, v237, s[2:3] offset:576
	v_mov_b32_e32 v172, v168
	v_mov_b32_e32 v173, v169
	v_mov_b32_e32 v174, v170
	v_mov_b32_e32 v175, v171
	global_load_dword v128, v172, s[36:37]
	global_load_dword v129, v173, s[36:37]
	global_load_dword v130, v174, s[36:37]
	global_load_dword v131, v175, s[36:37]
	global_load_dword v132, v172, s[36:37] offset:64
	global_load_dword v133, v173, s[36:37] offset:64
	global_load_dword v134, v174, s[36:37] offset:64
	global_load_dword v135, v175, s[36:37] offset:64
	global_load_dword v136, v172, s[36:37] offset:512
	global_load_dword v137, v173, s[36:37] offset:512
	global_load_dword v138, v174, s[36:37] offset:512
	global_load_dword v139, v175, s[36:37] offset:512
	global_load_dword v140, v172, s[36:37] offset:576
	global_load_dword v141, v173, s[36:37] offset:576
	global_load_dword v142, v174, s[36:37] offset:576
	global_load_dword v143, v175, s[36:37] offset:576
	v_add_u32_e32 v176, 0x20000, v168
	v_add_u32_e32 v177, 0x20000, v169
	v_add_u32_e32 v178, 0x20000, v170
	v_add_u32_e32 v179, 0x20000, v171
	global_load_dword v144, v176, s[36:37]
	global_load_dword v145, v177, s[36:37]
	global_load_dword v146, v178, s[36:37]
	global_load_dword v147, v179, s[36:37]
	global_load_dword v148, v176, s[36:37] offset:64
	global_load_dword v149, v177, s[36:37] offset:64
	global_load_dword v150, v178, s[36:37] offset:64
	global_load_dword v151, v179, s[36:37] offset:64
	global_load_dword v152, v176, s[36:37] offset:512
	global_load_dword v153, v177, s[36:37] offset:512
	global_load_dword v154, v178, s[36:37] offset:512
	global_load_dword v155, v179, s[36:37] offset:512
	global_load_dword v156, v176, s[36:37] offset:576
	global_load_dword v157, v177, s[36:37] offset:576
	global_load_dword v158, v178, s[36:37] offset:576
	global_load_dword v159, v179, s[36:37] offset:576
.Lgo_fz_w2:
	s_barrier
	s_cmp_lt_u32 s32, 0x100
	s_cbranch_scc0 .Lgo_fz_w3
	s_lshl_b32 s0, s45, 13
	v_add_u32_e32 v244, s0, v238
	v_add_u32_e32 v245, 0x1000, v244
	global_load_dword v246, v244, s[94:95] sc0 sc1
	global_load_dword v247, v244, s[94:95] offset:1024 sc0 sc1
	global_load_dword v248, v244, s[94:95] offset:2048 sc0 sc1
	global_load_dword v249, v244, s[94:95] offset:3072 sc0 sc1
	global_load_dword v250, v245, s[94:95] sc0 sc1
	global_load_dword v251, v245, s[94:95] offset:1024 sc0 sc1
	global_load_dword v252, v245, s[94:95] offset:2048 sc0 sc1
	global_load_dword v253, v245, s[94:95] offset:3072 sc0 sc1
	s_waitcnt vmcnt(0)
	v_add_f32_e32 v246, v246, v247
	v_add_f32_e32 v246, v246, v248
	v_add_f32_e32 v246, v246, v249
	v_add_f32_e32 v246, v246, v250
	v_add_f32_e32 v246, v246, v251
	v_add_f32_e32 v246, v246, v252
	v_add_f32_e32 v246, v246, v253
	v_fmamk_f32 v246, v246, 0x3a000000, v166
	v_mul_f32_e32 v247, 0x4b800000, v246
	v_cmp_gt_f32_e32 vcc, s58, v246
	s_nop 1
	v_cndmask_b32_e32 v246, v246, v247, vcc
	v_rsq_f32_e32 v248, v246
	s_nop 0
	v_mul_f32_e32 v247, 0x45800000, v248
	v_cndmask_b32_e32 v248, v248, v247, vcc
	ds_write_b32 v239, v248
	s_waitcnt lgkmcnt(0)
.Lgo_fz_w3:
	s_barrier
	v_lshlrev_b32_e32 v236, 2, v163
	v_add_u32_e32 v236, 0x20000, v236
	ds_read_b128 v[194:197], v236
	ds_read_b128 v[198:201], v236 offset:64
	ds_read_b128 v[202:205], v236 offset:128
	ds_read_b128 v[206:209], v236 offset:192
	ds_read_b128 v[210:213], v236 offset:512
	ds_read_b128 v[214:217], v236 offset:576
	ds_read_b128 v[218:221], v236 offset:640
	ds_read_b128 v[222:225], v236 offset:704
	s_waitcnt lgkmcnt(0)
	s_waitcnt vmcnt(16)
	v_mul_f32_e32 v124, v124, v226
	v_mul_f32_e32 v124, v124, v194
	v_fma_f32 v124, v124, v230, v128
	v_mul_f32_e32 v125, v125, v226
	v_mul_f32_e32 v125, v125, v195
	v_fma_f32 v125, v125, v230, v129
	v_mul_f32_e32 v126, v126, v226
	v_mul_f32_e32 v126, v126, v196
	v_fma_f32 v126, v126, v230, v130
	v_mul_f32_e32 v127, v127, v226
	v_mul_f32_e32 v127, v127, v197
	v_fma_f32 v127, v127, v230, v131
	v_mul_f32_e32 v120, v120, v227
	v_mul_f32_e32 v120, v120, v194
	v_fma_f32 v120, v120, v231, v132
	v_mul_f32_e32 v121, v121, v227
	v_mul_f32_e32 v121, v121, v195
	v_fma_f32 v121, v121, v231, v133
	v_mul_f32_e32 v122, v122, v227
	v_mul_f32_e32 v122, v122, v196
	v_fma_f32 v122, v122, v231, v134
	v_mul_f32_e32 v123, v123, v227
	v_mul_f32_e32 v123, v123, v197
	v_fma_f32 v123, v123, v231, v135
	v_mul_f32_e32 v100, v100, v228
	v_mul_f32_e32 v100, v100, v194
	v_fma_f32 v100, v100, v232, v136
	v_mul_f32_e32 v101, v101, v228
	v_mul_f32_e32 v101, v101, v195
	v_fma_f32 v101, v101, v232, v137
	v_mul_f32_e32 v102, v102, v228
	v_mul_f32_e32 v102, v102, v196
	v_fma_f32 v102, v102, v232, v138
	v_mul_f32_e32 v103, v103, v228
	v_mul_f32_e32 v103, v103, v197
	v_fma_f32 v103, v103, v232, v139
	v_mul_f32_e32 v96, v96, v229
	v_mul_f32_e32 v96, v96, v194
	v_fma_f32 v96, v96, v233, v140
	v_mul_f32_e32 v97, v97, v229
	v_mul_f32_e32 v97, v97, v195
	v_fma_f32 v97, v97, v233, v141
	v_mul_f32_e32 v98, v98, v229
	v_mul_f32_e32 v98, v98, v196
	v_fma_f32 v98, v98, v233, v142
	v_mul_f32_e32 v99, v99, v229
	v_mul_f32_e32 v99, v99, v197
	v_fma_f32 v99, v99, v233, v143
	global_store_dword v172, v124, s[36:37]
	global_store_dword v173, v125, s[36:37]
	global_store_dword v174, v126, s[36:37]
	global_store_dword v175, v127, s[36:37]
	global_store_dword v172, v120, s[36:37] offset:64
	global_store_dword v173, v121, s[36:37] offset:64
	global_store_dword v174, v122, s[36:37] offset:64
	global_store_dword v175, v123, s[36:37] offset:64
	global_store_dword v172, v100, s[36:37] offset:512
	global_store_dword v173, v101, s[36:37] offset:512
	global_store_dword v174, v102, s[36:37] offset:512
	global_store_dword v175, v103, s[36:37] offset:512
	global_store_dword v172, v96, s[36:37] offset:576
	global_store_dword v173, v97, s[36:37] offset:576
	global_store_dword v174, v98, s[36:37] offset:576
	global_store_dword v175, v99, s[36:37] offset:576
	v_add_u32_e32 v172, 0x40000, v168
	v_add_u32_e32 v173, 0x40000, v169
	v_add_u32_e32 v174, 0x40000, v170
	v_add_u32_e32 v175, 0x40000, v171
	global_load_dword v128, v172, s[36:37]
	global_load_dword v129, v173, s[36:37]
	global_load_dword v130, v174, s[36:37]
	global_load_dword v131, v175, s[36:37]
	global_load_dword v132, v172, s[36:37] offset:64
	global_load_dword v133, v173, s[36:37] offset:64
	global_load_dword v134, v174, s[36:37] offset:64
	global_load_dword v135, v175, s[36:37] offset:64
	global_load_dword v136, v172, s[36:37] offset:512
	global_load_dword v137, v173, s[36:37] offset:512
	global_load_dword v138, v174, s[36:37] offset:512
	global_load_dword v139, v175, s[36:37] offset:512
	global_load_dword v140, v172, s[36:37] offset:576
	global_load_dword v141, v173, s[36:37] offset:576
	global_load_dword v142, v174, s[36:37] offset:576
	global_load_dword v143, v175, s[36:37] offset:576
	s_waitcnt vmcnt(32)
	v_mul_f32_e32 v116, v116, v226
	v_mul_f32_e32 v116, v116, v198
	v_fma_f32 v116, v116, v230, v144
	v_mul_f32_e32 v117, v117, v226
	v_mul_f32_e32 v117, v117, v199
	v_fma_f32 v117, v117, v230, v145
	v_mul_f32_e32 v118, v118, v226
	v_mul_f32_e32 v118, v118, v200
	v_fma_f32 v118, v118, v230, v146
	v_mul_f32_e32 v119, v119, v226
	v_mul_f32_e32 v119, v119, v201
	v_fma_f32 v119, v119, v230, v147
	v_mul_f32_e32 v112, v112, v227
	v_mul_f32_e32 v112, v112, v198
	v_fma_f32 v112, v112, v231, v148
	v_mul_f32_e32 v113, v113, v227
	v_mul_f32_e32 v113, v113, v199
	v_fma_f32 v113, v113, v231, v149
	v_mul_f32_e32 v114, v114, v227
	v_mul_f32_e32 v114, v114, v200
	v_fma_f32 v114, v114, v231, v150
	v_mul_f32_e32 v115, v115, v227
	v_mul_f32_e32 v115, v115, v201
	v_fma_f32 v115, v115, v231, v151
	v_mul_f32_e32 v92, v92, v228
	v_mul_f32_e32 v92, v92, v198
	v_fma_f32 v92, v92, v232, v152
	v_mul_f32_e32 v93, v93, v228
	v_mul_f32_e32 v93, v93, v199
	v_fma_f32 v93, v93, v232, v153
	v_mul_f32_e32 v94, v94, v228
	v_mul_f32_e32 v94, v94, v200
	v_fma_f32 v94, v94, v232, v154
	v_mul_f32_e32 v95, v95, v228
	v_mul_f32_e32 v95, v95, v201
	v_fma_f32 v95, v95, v232, v155
	v_mul_f32_e32 v88, v88, v229
	v_mul_f32_e32 v88, v88, v198
	v_fma_f32 v88, v88, v233, v156
	v_mul_f32_e32 v89, v89, v229
	v_mul_f32_e32 v89, v89, v199
	v_fma_f32 v89, v89, v233, v157
	v_mul_f32_e32 v90, v90, v229
	v_mul_f32_e32 v90, v90, v200
	v_fma_f32 v90, v90, v233, v158
	v_mul_f32_e32 v91, v91, v229
	v_mul_f32_e32 v91, v91, v201
	v_fma_f32 v91, v91, v233, v159
	global_store_dword v176, v116, s[36:37]
	global_store_dword v177, v117, s[36:37]
	global_store_dword v178, v118, s[36:37]
	global_store_dword v179, v119, s[36:37]
	global_store_dword v176, v112, s[36:37] offset:64
	global_store_dword v177, v113, s[36:37] offset:64
	global_store_dword v178, v114, s[36:37] offset:64
	global_store_dword v179, v115, s[36:37] offset:64
	global_store_dword v176, v92, s[36:37] offset:512
	global_store_dword v177, v93, s[36:37] offset:512
	global_store_dword v178, v94, s[36:37] offset:512
	global_store_dword v179, v95, s[36:37] offset:512
	global_store_dword v176, v88, s[36:37] offset:576
	global_store_dword v177, v89, s[36:37] offset:576
	global_store_dword v178, v90, s[36:37] offset:576
	global_store_dword v179, v91, s[36:37] offset:576
	v_add_u32_e32 v176, 0x60000, v168
	v_add_u32_e32 v177, 0x60000, v169
	v_add_u32_e32 v178, 0x60000, v170
	v_add_u32_e32 v179, 0x60000, v171
	global_load_dword v144, v176, s[36:37]
	global_load_dword v145, v177, s[36:37]
	global_load_dword v146, v178, s[36:37]
	global_load_dword v147, v179, s[36:37]
	global_load_dword v148, v176, s[36:37] offset:64
	global_load_dword v149, v177, s[36:37] offset:64
	global_load_dword v150, v178, s[36:37] offset:64
	global_load_dword v151, v179, s[36:37] offset:64
	global_load_dword v152, v176, s[36:37] offset:512
	global_load_dword v153, v177, s[36:37] offset:512
	global_load_dword v154, v178, s[36:37] offset:512
	global_load_dword v155, v179, s[36:37] offset:512
	global_load_dword v156, v176, s[36:37] offset:576
	global_load_dword v157, v177, s[36:37] offset:576
	global_load_dword v158, v178, s[36:37] offset:576
	global_load_dword v159, v179, s[36:37] offset:576
	s_waitcnt vmcnt(32)
	v_mul_f32_e32 v108, v108, v226
	v_mul_f32_e32 v108, v108, v202
	v_fma_f32 v108, v108, v230, v128
	v_mul_f32_e32 v109, v109, v226
	v_mul_f32_e32 v109, v109, v203
	v_fma_f32 v109, v109, v230, v129
	v_mul_f32_e32 v110, v110, v226
	v_mul_f32_e32 v110, v110, v204
	v_fma_f32 v110, v110, v230, v130
	v_mul_f32_e32 v111, v111, v226
	v_mul_f32_e32 v111, v111, v205
	v_fma_f32 v111, v111, v230, v131
	v_mul_f32_e32 v104, v104, v227
	v_mul_f32_e32 v104, v104, v202
	v_fma_f32 v104, v104, v231, v132
	v_mul_f32_e32 v105, v105, v227
	v_mul_f32_e32 v105, v105, v203
	v_fma_f32 v105, v105, v231, v133
	v_mul_f32_e32 v106, v106, v227
	v_mul_f32_e32 v106, v106, v204
	v_fma_f32 v106, v106, v231, v134
	v_mul_f32_e32 v107, v107, v227
	v_mul_f32_e32 v107, v107, v205
	v_fma_f32 v107, v107, v231, v135
	v_mul_f32_e32 v80, v80, v228
	v_mul_f32_e32 v80, v80, v202
	v_fma_f32 v80, v80, v232, v136
	v_mul_f32_e32 v81, v81, v228
	v_mul_f32_e32 v81, v81, v203
	v_fma_f32 v81, v81, v232, v137
	v_mul_f32_e32 v82, v82, v228
	v_mul_f32_e32 v82, v82, v204
	v_fma_f32 v82, v82, v232, v138
	v_mul_f32_e32 v83, v83, v228
	v_mul_f32_e32 v83, v83, v205
	v_fma_f32 v83, v83, v232, v139
	v_mul_f32_e32 v72, v72, v229
	v_mul_f32_e32 v72, v72, v202
	v_fma_f32 v72, v72, v233, v140
	v_mul_f32_e32 v73, v73, v229
	v_mul_f32_e32 v73, v73, v203
	v_fma_f32 v73, v73, v233, v141
	v_mul_f32_e32 v74, v74, v229
	v_mul_f32_e32 v74, v74, v204
	v_fma_f32 v74, v74, v233, v142
	v_mul_f32_e32 v75, v75, v229
	v_mul_f32_e32 v75, v75, v205
	v_fma_f32 v75, v75, v233, v143
	global_store_dword v172, v108, s[36:37]
	global_store_dword v173, v109, s[36:37]
	global_store_dword v174, v110, s[36:37]
	global_store_dword v175, v111, s[36:37]
	global_store_dword v172, v104, s[36:37] offset:64
	global_store_dword v173, v105, s[36:37] offset:64
	global_store_dword v174, v106, s[36:37] offset:64
	global_store_dword v175, v107, s[36:37] offset:64
	global_store_dword v172, v80, s[36:37] offset:512
	global_store_dword v173, v81, s[36:37] offset:512
	global_store_dword v174, v82, s[36:37] offset:512
	global_store_dword v175, v83, s[36:37] offset:512
	global_store_dword v172, v72, s[36:37] offset:576
	global_store_dword v173, v73, s[36:37] offset:576
	global_store_dword v174, v74, s[36:37] offset:576
	global_store_dword v175, v75, s[36:37] offset:576
	v_add_u32_e32 v172, 0x100000, v168
	v_add_u32_e32 v173, 0x100000, v169
	v_add_u32_e32 v174, 0x100000, v170
	v_add_u32_e32 v175, 0x100000, v171
	global_load_dword v128, v172, s[36:37]
	global_load_dword v129, v173, s[36:37]
	global_load_dword v130, v174, s[36:37]
	global_load_dword v131, v175, s[36:37]
	global_load_dword v132, v172, s[36:37] offset:64
	global_load_dword v133, v173, s[36:37] offset:64
	global_load_dword v134, v174, s[36:37] offset:64
	global_load_dword v135, v175, s[36:37] offset:64
	global_load_dword v136, v172, s[36:37] offset:512
	global_load_dword v137, v173, s[36:37] offset:512
	global_load_dword v138, v174, s[36:37] offset:512
	global_load_dword v139, v175, s[36:37] offset:512
	global_load_dword v140, v172, s[36:37] offset:576
	global_load_dword v141, v173, s[36:37] offset:576
	global_load_dword v142, v174, s[36:37] offset:576
	global_load_dword v143, v175, s[36:37] offset:576
	s_waitcnt vmcnt(32)
	v_mul_f32_e32 v84, v84, v226
	v_mul_f32_e32 v84, v84, v206
	v_fma_f32 v84, v84, v230, v144
	v_mul_f32_e32 v85, v85, v226
	v_mul_f32_e32 v85, v85, v207
	v_fma_f32 v85, v85, v230, v145
	v_mul_f32_e32 v86, v86, v226
	v_mul_f32_e32 v86, v86, v208
	v_fma_f32 v86, v86, v230, v146
	v_mul_f32_e32 v87, v87, v226
	v_mul_f32_e32 v87, v87, v209
	v_fma_f32 v87, v87, v230, v147
	v_mul_f32_e32 v76, v76, v227
	v_mul_f32_e32 v76, v76, v206
	v_fma_f32 v76, v76, v231, v148
	v_mul_f32_e32 v77, v77, v227
	v_mul_f32_e32 v77, v77, v207
	v_fma_f32 v77, v77, v231, v149
	v_mul_f32_e32 v78, v78, v227
	v_mul_f32_e32 v78, v78, v208
	v_fma_f32 v78, v78, v231, v150
	v_mul_f32_e32 v79, v79, v227
	v_mul_f32_e32 v79, v79, v209
	v_fma_f32 v79, v79, v231, v151
	v_mul_f32_e32 v68, v68, v228
	v_mul_f32_e32 v68, v68, v206
	v_fma_f32 v68, v68, v232, v152
	v_mul_f32_e32 v69, v69, v228
	v_mul_f32_e32 v69, v69, v207
	v_fma_f32 v69, v69, v232, v153
	v_mul_f32_e32 v70, v70, v228
	v_mul_f32_e32 v70, v70, v208
	v_fma_f32 v70, v70, v232, v154
	v_mul_f32_e32 v71, v71, v228
	v_mul_f32_e32 v71, v71, v209
	v_fma_f32 v71, v71, v232, v155
	v_mul_f32_e32 v64, v64, v229
	v_mul_f32_e32 v64, v64, v206
	v_fma_f32 v64, v64, v233, v156
	v_mul_f32_e32 v65, v65, v229
	v_mul_f32_e32 v65, v65, v207
	v_fma_f32 v65, v65, v233, v157
	v_mul_f32_e32 v66, v66, v229
	v_mul_f32_e32 v66, v66, v208
	v_fma_f32 v66, v66, v233, v158
	v_mul_f32_e32 v67, v67, v229
	v_mul_f32_e32 v67, v67, v209
	v_fma_f32 v67, v67, v233, v159
	global_store_dword v176, v84, s[36:37]
	global_store_dword v177, v85, s[36:37]
	global_store_dword v178, v86, s[36:37]
	global_store_dword v179, v87, s[36:37]
	global_store_dword v176, v76, s[36:37] offset:64
	global_store_dword v177, v77, s[36:37] offset:64
	global_store_dword v178, v78, s[36:37] offset:64
	global_store_dword v179, v79, s[36:37] offset:64
	global_store_dword v176, v68, s[36:37] offset:512
	global_store_dword v177, v69, s[36:37] offset:512
	global_store_dword v178, v70, s[36:37] offset:512
	global_store_dword v179, v71, s[36:37] offset:512
	global_store_dword v176, v64, s[36:37] offset:576
	global_store_dword v177, v65, s[36:37] offset:576
	global_store_dword v178, v66, s[36:37] offset:576
	global_store_dword v179, v67, s[36:37] offset:576
	v_add_u32_e32 v176, 0x120000, v168
	v_add_u32_e32 v177, 0x120000, v169
	v_add_u32_e32 v178, 0x120000, v170
	v_add_u32_e32 v179, 0x120000, v171
	global_load_dword v144, v176, s[36:37]
	global_load_dword v145, v177, s[36:37]
	global_load_dword v146, v178, s[36:37]
	global_load_dword v147, v179, s[36:37]
	global_load_dword v148, v176, s[36:37] offset:64
	global_load_dword v149, v177, s[36:37] offset:64
	global_load_dword v150, v178, s[36:37] offset:64
	global_load_dword v151, v179, s[36:37] offset:64
	global_load_dword v152, v176, s[36:37] offset:512
	global_load_dword v153, v177, s[36:37] offset:512
	global_load_dword v154, v178, s[36:37] offset:512
	global_load_dword v155, v179, s[36:37] offset:512
	global_load_dword v156, v176, s[36:37] offset:576
	global_load_dword v157, v177, s[36:37] offset:576
	global_load_dword v158, v178, s[36:37] offset:576
	global_load_dword v159, v179, s[36:37] offset:576
	s_waitcnt vmcnt(32)
	v_mul_f32_e32 v60, v60, v226
	v_mul_f32_e32 v60, v60, v210
	v_fma_f32 v60, v60, v230, v128
	v_mul_f32_e32 v61, v61, v226
	v_mul_f32_e32 v61, v61, v211
	v_fma_f32 v61, v61, v230, v129
	v_mul_f32_e32 v62, v62, v226
	v_mul_f32_e32 v62, v62, v212
	v_fma_f32 v62, v62, v230, v130
	v_mul_f32_e32 v63, v63, v226
	v_mul_f32_e32 v63, v63, v213
	v_fma_f32 v63, v63, v230, v131
	v_mul_f32_e32 v56, v56, v227
	v_mul_f32_e32 v56, v56, v210
	v_fma_f32 v56, v56, v231, v132
	v_mul_f32_e32 v57, v57, v227
	v_mul_f32_e32 v57, v57, v211
	v_fma_f32 v57, v57, v231, v133
	v_mul_f32_e32 v58, v58, v227
	v_mul_f32_e32 v58, v58, v212
	v_fma_f32 v58, v58, v231, v134
	v_mul_f32_e32 v59, v59, v227
	v_mul_f32_e32 v59, v59, v213
	v_fma_f32 v59, v59, v231, v135
	v_mul_f32_e32 v32, v32, v228
	v_mul_f32_e32 v32, v32, v210
	v_fma_f32 v32, v32, v232, v136
	v_mul_f32_e32 v33, v33, v228
	v_mul_f32_e32 v33, v33, v211
	v_fma_f32 v33, v33, v232, v137
	v_mul_f32_e32 v34, v34, v228
	v_mul_f32_e32 v34, v34, v212
	v_fma_f32 v34, v34, v232, v138
	v_mul_f32_e32 v35, v35, v228
	v_mul_f32_e32 v35, v35, v213
	v_fma_f32 v35, v35, v232, v139
	v_mul_f32_e32 v24, v24, v229
	v_mul_f32_e32 v24, v24, v210
	v_fma_f32 v24, v24, v233, v140
	v_mul_f32_e32 v25, v25, v229
	v_mul_f32_e32 v25, v25, v211
	v_fma_f32 v25, v25, v233, v141
	v_mul_f32_e32 v26, v26, v229
	v_mul_f32_e32 v26, v26, v212
	v_fma_f32 v26, v26, v233, v142
	v_mul_f32_e32 v27, v27, v229
	v_mul_f32_e32 v27, v27, v213
	v_fma_f32 v27, v27, v233, v143
	global_store_dword v172, v60, s[36:37]
	global_store_dword v173, v61, s[36:37]
	global_store_dword v174, v62, s[36:37]
	global_store_dword v175, v63, s[36:37]
	global_store_dword v172, v56, s[36:37] offset:64
	global_store_dword v173, v57, s[36:37] offset:64
	global_store_dword v174, v58, s[36:37] offset:64
	global_store_dword v175, v59, s[36:37] offset:64
	global_store_dword v172, v32, s[36:37] offset:512
	global_store_dword v173, v33, s[36:37] offset:512
	global_store_dword v174, v34, s[36:37] offset:512
	global_store_dword v175, v35, s[36:37] offset:512
	global_store_dword v172, v24, s[36:37] offset:576
	global_store_dword v173, v25, s[36:37] offset:576
	global_store_dword v174, v26, s[36:37] offset:576
	global_store_dword v175, v27, s[36:37] offset:576
	v_add_u32_e32 v172, 0x140000, v168
	v_add_u32_e32 v173, 0x140000, v169
	v_add_u32_e32 v174, 0x140000, v170
	v_add_u32_e32 v175, 0x140000, v171
	global_load_dword v128, v172, s[36:37]
	global_load_dword v129, v173, s[36:37]
	global_load_dword v130, v174, s[36:37]
	global_load_dword v131, v175, s[36:37]
	global_load_dword v132, v172, s[36:37] offset:64
	global_load_dword v133, v173, s[36:37] offset:64
	global_load_dword v134, v174, s[36:37] offset:64
	global_load_dword v135, v175, s[36:37] offset:64
	global_load_dword v136, v172, s[36:37] offset:512
	global_load_dword v137, v173, s[36:37] offset:512
	global_load_dword v138, v174, s[36:37] offset:512
	global_load_dword v139, v175, s[36:37] offset:512
	global_load_dword v140, v172, s[36:37] offset:576
	global_load_dword v141, v173, s[36:37] offset:576
	global_load_dword v142, v174, s[36:37] offset:576
	global_load_dword v143, v175, s[36:37] offset:576
	s_waitcnt vmcnt(32)
	v_mul_f32_e32 v52, v52, v226
	v_mul_f32_e32 v52, v52, v214
	v_fma_f32 v52, v52, v230, v144
	v_mul_f32_e32 v53, v53, v226
	v_mul_f32_e32 v53, v53, v215
	v_fma_f32 v53, v53, v230, v145
	v_mul_f32_e32 v54, v54, v226
	v_mul_f32_e32 v54, v54, v216
	v_fma_f32 v54, v54, v230, v146
	v_mul_f32_e32 v55, v55, v226
	v_mul_f32_e32 v55, v55, v217
	v_fma_f32 v55, v55, v230, v147
	v_mul_f32_e32 v48, v48, v227
	v_mul_f32_e32 v48, v48, v214
	v_fma_f32 v48, v48, v231, v148
	v_mul_f32_e32 v49, v49, v227
	v_mul_f32_e32 v49, v49, v215
	v_fma_f32 v49, v49, v231, v149
	v_mul_f32_e32 v50, v50, v227
	v_mul_f32_e32 v50, v50, v216
	v_fma_f32 v50, v50, v231, v150
	v_mul_f32_e32 v51, v51, v227
	v_mul_f32_e32 v51, v51, v217
	v_fma_f32 v51, v51, v231, v151
	v_mul_f32_e32 v20, v20, v228
	v_mul_f32_e32 v20, v20, v214
	v_fma_f32 v20, v20, v232, v152
	v_mul_f32_e32 v21, v21, v228
	v_mul_f32_e32 v21, v21, v215
	v_fma_f32 v21, v21, v232, v153
	v_mul_f32_e32 v22, v22, v228
	v_mul_f32_e32 v22, v22, v216
	v_fma_f32 v22, v22, v232, v154
	v_mul_f32_e32 v23, v23, v228
	v_mul_f32_e32 v23, v23, v217
	v_fma_f32 v23, v23, v232, v155
	v_mul_f32_e32 v16, v16, v229
	v_mul_f32_e32 v16, v16, v214
	v_fma_f32 v16, v16, v233, v156
	v_mul_f32_e32 v17, v17, v229
	v_mul_f32_e32 v17, v17, v215
	v_fma_f32 v17, v17, v233, v157
	v_mul_f32_e32 v18, v18, v229
	v_mul_f32_e32 v18, v18, v216
	v_fma_f32 v18, v18, v233, v158
	v_mul_f32_e32 v19, v19, v229
	v_mul_f32_e32 v19, v19, v217
	v_fma_f32 v19, v19, v233, v159
	global_store_dword v176, v52, s[36:37]
	global_store_dword v177, v53, s[36:37]
	global_store_dword v178, v54, s[36:37]
	global_store_dword v179, v55, s[36:37]
	global_store_dword v176, v48, s[36:37] offset:64
	global_store_dword v177, v49, s[36:37] offset:64
	global_store_dword v178, v50, s[36:37] offset:64
	global_store_dword v179, v51, s[36:37] offset:64
	global_store_dword v176, v20, s[36:37] offset:512
	global_store_dword v177, v21, s[36:37] offset:512
	global_store_dword v178, v22, s[36:37] offset:512
	global_store_dword v179, v23, s[36:37] offset:512
	global_store_dword v176, v16, s[36:37] offset:576
	global_store_dword v177, v17, s[36:37] offset:576
	global_store_dword v178, v18, s[36:37] offset:576
	global_store_dword v179, v19, s[36:37] offset:576
	v_add_u32_e32 v176, 0x160000, v168
	v_add_u32_e32 v177, 0x160000, v169
	v_add_u32_e32 v178, 0x160000, v170
	v_add_u32_e32 v179, 0x160000, v171
	global_load_dword v144, v176, s[36:37]
	global_load_dword v145, v177, s[36:37]
	global_load_dword v146, v178, s[36:37]
	global_load_dword v147, v179, s[36:37]
	global_load_dword v148, v176, s[36:37] offset:64
	global_load_dword v149, v177, s[36:37] offset:64
	global_load_dword v150, v178, s[36:37] offset:64
	global_load_dword v151, v179, s[36:37] offset:64
	global_load_dword v152, v176, s[36:37] offset:512
	global_load_dword v153, v177, s[36:37] offset:512
	global_load_dword v154, v178, s[36:37] offset:512
	global_load_dword v155, v179, s[36:37] offset:512
	global_load_dword v156, v176, s[36:37] offset:576
	global_load_dword v157, v177, s[36:37] offset:576
	global_load_dword v158, v178, s[36:37] offset:576
	global_load_dword v159, v179, s[36:37] offset:576
	s_waitcnt vmcnt(32)
	v_mul_f32_e32 v44, v44, v226
	v_mul_f32_e32 v44, v44, v218
	v_fma_f32 v44, v44, v230, v128
	v_mul_f32_e32 v45, v45, v226
	v_mul_f32_e32 v45, v45, v219
	v_fma_f32 v45, v45, v230, v129
	v_mul_f32_e32 v46, v46, v226
	v_mul_f32_e32 v46, v46, v220
	v_fma_f32 v46, v46, v230, v130
	v_mul_f32_e32 v47, v47, v226
	v_mul_f32_e32 v47, v47, v221
	v_fma_f32 v47, v47, v230, v131
	v_mul_f32_e32 v40, v40, v227
	v_mul_f32_e32 v40, v40, v218
	v_fma_f32 v40, v40, v231, v132
	v_mul_f32_e32 v41, v41, v227
	v_mul_f32_e32 v41, v41, v219
	v_fma_f32 v41, v41, v231, v133
	v_mul_f32_e32 v42, v42, v227
	v_mul_f32_e32 v42, v42, v220
	v_fma_f32 v42, v42, v231, v134
	v_mul_f32_e32 v43, v43, v227
	v_mul_f32_e32 v43, v43, v221
	v_fma_f32 v43, v43, v231, v135
	v_mul_f32_e32 v12, v12, v228
	v_mul_f32_e32 v12, v12, v218
	v_fma_f32 v12, v12, v232, v136
	v_mul_f32_e32 v13, v13, v228
	v_mul_f32_e32 v13, v13, v219
	v_fma_f32 v13, v13, v232, v137
	v_mul_f32_e32 v14, v14, v228
	v_mul_f32_e32 v14, v14, v220
	v_fma_f32 v14, v14, v232, v138
	v_mul_f32_e32 v15, v15, v228
	v_mul_f32_e32 v15, v15, v221
	v_fma_f32 v15, v15, v232, v139
	v_mul_f32_e32 v8, v8, v229
	v_mul_f32_e32 v8, v8, v218
	v_fma_f32 v8, v8, v233, v140
	v_mul_f32_e32 v9, v9, v229
	v_mul_f32_e32 v9, v9, v219
	v_fma_f32 v9, v9, v233, v141
	v_mul_f32_e32 v10, v10, v229
	v_mul_f32_e32 v10, v10, v220
	v_fma_f32 v10, v10, v233, v142
	v_mul_f32_e32 v11, v11, v229
	v_mul_f32_e32 v11, v11, v221
	v_fma_f32 v11, v11, v233, v143
	global_store_dword v172, v44, s[36:37]
	global_store_dword v173, v45, s[36:37]
	global_store_dword v174, v46, s[36:37]
	global_store_dword v175, v47, s[36:37]
	global_store_dword v172, v40, s[36:37] offset:64
	global_store_dword v173, v41, s[36:37] offset:64
	global_store_dword v174, v42, s[36:37] offset:64
	global_store_dword v175, v43, s[36:37] offset:64
	global_store_dword v172, v12, s[36:37] offset:512
	global_store_dword v173, v13, s[36:37] offset:512
	global_store_dword v174, v14, s[36:37] offset:512
	global_store_dword v175, v15, s[36:37] offset:512
	global_store_dword v172, v8, s[36:37] offset:576
	global_store_dword v173, v9, s[36:37] offset:576
	global_store_dword v174, v10, s[36:37] offset:576
	global_store_dword v175, v11, s[36:37] offset:576
	s_waitcnt vmcnt(16)
	v_mul_f32_e32 v36, v36, v226
	v_mul_f32_e32 v36, v36, v222
	v_fma_f32 v36, v36, v230, v144
	v_mul_f32_e32 v37, v37, v226
	v_mul_f32_e32 v37, v37, v223
	v_fma_f32 v37, v37, v230, v145
	v_mul_f32_e32 v38, v38, v226
	v_mul_f32_e32 v38, v38, v224
	v_fma_f32 v38, v38, v230, v146
	v_mul_f32_e32 v39, v39, v226
	v_mul_f32_e32 v39, v39, v225
	v_fma_f32 v39, v39, v230, v147
	v_mul_f32_e32 v28, v28, v227
	v_mul_f32_e32 v28, v28, v222
	v_fma_f32 v28, v28, v231, v148
	v_mul_f32_e32 v29, v29, v227
	v_mul_f32_e32 v29, v29, v223
	v_fma_f32 v29, v29, v231, v149
	v_mul_f32_e32 v30, v30, v227
	v_mul_f32_e32 v30, v30, v224
	v_fma_f32 v30, v30, v231, v150
	v_mul_f32_e32 v31, v31, v227
	v_mul_f32_e32 v31, v31, v225
	v_fma_f32 v31, v31, v231, v151
	v_mul_f32_e32 v4, v4, v228
	v_mul_f32_e32 v4, v4, v222
	v_fma_f32 v4, v4, v232, v152
	v_mul_f32_e32 v5, v5, v228
	v_mul_f32_e32 v5, v5, v223
	v_fma_f32 v5, v5, v232, v153
	v_mul_f32_e32 v6, v6, v228
	v_mul_f32_e32 v6, v6, v224
	v_fma_f32 v6, v6, v232, v154
	v_mul_f32_e32 v7, v7, v228
	v_mul_f32_e32 v7, v7, v225
	v_fma_f32 v7, v7, v232, v155
	v_mul_f32_e32 v0, v0, v229
	v_mul_f32_e32 v0, v0, v222
	v_fma_f32 v0, v0, v233, v156
	v_mul_f32_e32 v1, v1, v229
	v_mul_f32_e32 v1, v1, v223
	v_fma_f32 v1, v1, v233, v157
	v_mul_f32_e32 v2, v2, v229
	v_mul_f32_e32 v2, v2, v224
	v_fma_f32 v2, v2, v233, v158
	v_mul_f32_e32 v3, v3, v229
	v_mul_f32_e32 v3, v3, v225
	v_fma_f32 v3, v3, v233, v159
	global_store_dword v176, v36, s[36:37]
	global_store_dword v177, v37, s[36:37]
	global_store_dword v178, v38, s[36:37]
	global_store_dword v179, v39, s[36:37]
	global_store_dword v176, v28, s[36:37] offset:64
	global_store_dword v177, v29, s[36:37] offset:64
	global_store_dword v178, v30, s[36:37] offset:64
	global_store_dword v179, v31, s[36:37] offset:64
	global_store_dword v176, v4, s[36:37] offset:512
	global_store_dword v177, v5, s[36:37] offset:512
	global_store_dword v178, v6, s[36:37] offset:512
	global_store_dword v179, v7, s[36:37] offset:512
	global_store_dword v176, v0, s[36:37] offset:576
	global_store_dword v177, v1, s[36:37] offset:576
	global_store_dword v178, v2, s[36:37] offset:576
	global_store_dword v179, v3, s[36:37] offset:576
	v_readlane_b32 s0, v254, 1
	s_add_i32 s44, s44, s0
	s_barrier
	v_readlane_b32 s1, v254, 2
	s_cmp_ge_i32 s44, s46
	s_cbranch_scc1 .LBB0_1172
